# FFN-up: conv weights for the epilogue loaded during the last K iteration (latency hidden behind the final MFMAs)
# baseline (speedup 1.0000x reference)
.LBB0_584:
	ds_read_b128 v[100:103], v193
	ds_read_b128 v[104:107], v193 offset:1024
	ds_read_b128 v[112:115], v193 offset:2048
	ds_read_b128 v[116:119], v193 offset:3072
	ds_read_b128 v[120:123], v194
	ds_read_b128 v[124:127], v194 offset:1024
	ds_read_b128 v[128:131], v194 offset:2048
	ds_read_b128 v[132:135], v194 offset:3072
	s_add_u32 s8, s10, 0x100
	s_addc_u32 s9, s11, 0
	s_cmp_eq_u32 s20, 12
	s_cselect_b32 s15, s81, s9
	s_cselect_b32 s14, s80, s8
	s_cselect_b32 s13, s1, s19
	s_cselect_b32 s12, s17, s18
	v_lshl_add_u64 v[222:223], s[10:11], 0, v[168:169]
	s_add_i32 m0, s53, 0xc000
	ds_read_b128 v[176:179], v195
	ds_read_b128 v[180:183], v195 offset:1024
	ds_read_b128 v[198:201], v195 offset:2048
	ds_read_b128 v[202:205], v195 offset:3072
	ds_read_b128 v[206:209], v195 offset:4096
	ds_read_b128 v[210:213], v195 offset:5120
	ds_read_b128 v[214:217], v195 offset:6144
	ds_read_b128 v[218:221], v195 offset:7168
	global_load_lds_dwordx4 v[222:223], off
	v_lshl_add_u64 v[222:223], s[10:11], 0, v[170:171]
	s_add_i32 m0, s53, 0xe000
	s_nop 0
	global_load_lds_dwordx4 v[222:223], off
	s_waitcnt vmcnt(8)
	s_waitcnt lgkmcnt(0)
	s_barrier
	s_setprio 1
	s_waitcnt lgkmcnt(0)
	v_mfma_f32_16x16x32_bf16 v[156:159], v[176:179], v[100:103], v[156:159]
	v_mfma_f32_16x16x32_bf16 v[60:63], v[176:179], v[112:115], v[60:63]
	v_mfma_f32_16x16x32_bf16 v[148:151], v[198:201], v[100:103], v[148:151]
	v_mfma_f32_16x16x32_bf16 v[52:55], v[198:201], v[112:115], v[52:55]
	v_mfma_f32_16x16x32_bf16 v[140:143], v[206:209], v[100:103], v[140:143]
	v_mfma_f32_16x16x32_bf16 v[44:47], v[206:209], v[112:115], v[44:47]
	v_mfma_f32_16x16x32_bf16 v[108:111], v[214:217], v[100:103], v[108:111]
	v_mfma_f32_16x16x32_bf16 v[36:39], v[214:217], v[112:115], v[36:39]
	v_mfma_f32_16x16x32_bf16 v[156:159], v[180:183], v[104:107], v[156:159]
	v_mfma_f32_16x16x32_bf16 v[60:63], v[180:183], v[116:119], v[60:63]
	v_mfma_f32_16x16x32_bf16 v[148:151], v[202:205], v[104:107], v[148:151]
	v_mfma_f32_16x16x32_bf16 v[52:55], v[202:205], v[116:119], v[52:55]
	v_mfma_f32_16x16x32_bf16 v[140:143], v[210:213], v[104:107], v[140:143]
	v_mfma_f32_16x16x32_bf16 v[44:47], v[210:213], v[116:119], v[44:47]
	v_mfma_f32_16x16x32_bf16 v[108:111], v[218:221], v[104:107], v[108:111]
	v_mfma_f32_16x16x32_bf16 v[36:39], v[218:221], v[116:119], v[36:39]
	s_setprio 0
	s_setprio 1
	v_mfma_f32_16x16x32_bf16 v[152:155], v[176:179], v[120:123], v[152:155]
	v_mfma_f32_16x16x32_bf16 v[56:59], v[176:179], v[128:131], v[56:59]
	v_mfma_f32_16x16x32_bf16 v[144:147], v[198:201], v[120:123], v[144:147]
	v_mfma_f32_16x16x32_bf16 v[48:51], v[198:201], v[128:131], v[48:51]
	v_mfma_f32_16x16x32_bf16 v[136:139], v[206:209], v[120:123], v[136:139]
	v_mfma_f32_16x16x32_bf16 v[40:43], v[206:209], v[128:131], v[40:43]
	v_mfma_f32_16x16x32_bf16 v[96:99], v[214:217], v[120:123], v[96:99]
	v_mfma_f32_16x16x32_bf16 v[32:35], v[214:217], v[128:131], v[32:35]
	v_mfma_f32_16x16x32_bf16 v[152:155], v[180:183], v[124:127], v[152:155]
	v_mfma_f32_16x16x32_bf16 v[56:59], v[180:183], v[132:135], v[56:59]
	v_mfma_f32_16x16x32_bf16 v[144:147], v[202:205], v[124:127], v[144:147]
	v_mfma_f32_16x16x32_bf16 v[48:51], v[202:205], v[132:135], v[48:51]
	v_mfma_f32_16x16x32_bf16 v[136:139], v[210:213], v[124:127], v[136:139]
	v_mfma_f32_16x16x32_bf16 v[40:43], v[210:213], v[132:135], v[40:43]
	v_mfma_f32_16x16x32_bf16 v[96:99], v[218:221], v[124:127], v[96:99]
	v_mfma_f32_16x16x32_bf16 v[32:35], v[218:221], v[132:135], v[32:35]
	s_setprio 0
	s_barrier
	s_add_i32 s10, s91, s52
	v_lshl_add_u64 v[222:223], s[12:13], 0, v[162:163]
	s_mov_b32 m0, s10
	ds_read_b128 v[176:179], v195 offset:16384
	ds_read_b128 v[180:183], v195 offset:17408
	ds_read_b128 v[198:201], v195 offset:18432
	ds_read_b128 v[202:205], v195 offset:19456
	ds_read_b128 v[206:209], v195 offset:20480
	ds_read_b128 v[210:213], v195 offset:21504
	ds_read_b128 v[214:217], v195 offset:22528
	ds_read_b128 v[218:221], v195 offset:23552
	global_load_lds_dwordx4 v[222:223], off
	s_add_i32 m0, s10, 0x2000
	s_add_u32 s10, s12, 0x580000
	v_lshl_add_u64 v[224:225], s[12:13], 0, v[166:167]
	s_addc_u32 s11, s13, 0
	s_add_i32 s21, s60, s52
	global_load_lds_dwordx4 v[224:225], off
	v_lshl_add_u64 v[226:227], s[10:11], 0, v[162:163]
	s_mov_b32 m0, s21
	v_lshl_add_u64 v[228:229], s[14:15], 0, v[164:165]
	global_load_lds_dwordx4 v[226:227], off
	v_lshl_add_u64 v[226:227], s[10:11], 0, v[166:167]
	s_add_i32 m0, s21, 0x2000
	s_nop 0
	global_load_lds_dwordx4 v[226:227], off
	v_lshl_add_u64 v[226:227], s[14:15], 0, v[160:161]
	s_mov_b32 m0, s53
	s_nop 0
	global_load_lds_dwordx4 v[226:227], off
	s_mov_b32 m0, s54
	s_nop 0
	global_load_lds_dwordx4 v[228:229], off
	s_waitcnt vmcnt(8)
	s_waitcnt lgkmcnt(0)
	s_barrier
	s_setprio 1
	s_waitcnt lgkmcnt(0)
	v_mfma_f32_16x16x32_bf16 v[92:95], v[176:179], v[100:103], v[92:95]
	v_mfma_f32_16x16x32_bf16 v[28:31], v[176:179], v[112:115], v[28:31]
	v_mfma_f32_16x16x32_bf16 v[84:87], v[198:201], v[100:103], v[84:87]
	v_mfma_f32_16x16x32_bf16 v[20:23], v[198:201], v[112:115], v[20:23]
	v_mfma_f32_16x16x32_bf16 v[76:79], v[206:209], v[100:103], v[76:79]
	v_mfma_f32_16x16x32_bf16 v[12:15], v[206:209], v[112:115], v[12:15]
	v_mfma_f32_16x16x32_bf16 v[68:71], v[214:217], v[100:103], v[68:71]
	v_mfma_f32_16x16x32_bf16 v[4:7], v[214:217], v[112:115], v[4:7]
	v_mfma_f32_16x16x32_bf16 v[92:95], v[180:183], v[104:107], v[92:95]
	v_mfma_f32_16x16x32_bf16 v[28:31], v[180:183], v[116:119], v[28:31]
	v_mfma_f32_16x16x32_bf16 v[84:87], v[202:205], v[104:107], v[84:87]
	v_mfma_f32_16x16x32_bf16 v[20:23], v[202:205], v[116:119], v[20:23]
	v_mfma_f32_16x16x32_bf16 v[76:79], v[210:213], v[104:107], v[76:79]
	v_mfma_f32_16x16x32_bf16 v[12:15], v[210:213], v[116:119], v[12:15]
	v_mfma_f32_16x16x32_bf16 v[68:71], v[218:221], v[104:107], v[68:71]
	v_mfma_f32_16x16x32_bf16 v[4:7], v[218:221], v[116:119], v[4:7]
	s_setprio 0
	s_setprio 1
	v_mfma_f32_16x16x32_bf16 v[88:91], v[176:179], v[120:123], v[88:91]
	v_mfma_f32_16x16x32_bf16 v[24:27], v[176:179], v[128:131], v[24:27]
	v_mfma_f32_16x16x32_bf16 v[80:83], v[198:201], v[120:123], v[80:83]
	v_mfma_f32_16x16x32_bf16 v[16:19], v[198:201], v[128:131], v[16:19]
	v_mfma_f32_16x16x32_bf16 v[72:75], v[206:209], v[120:123], v[72:75]
	v_mfma_f32_16x16x32_bf16 v[8:11], v[206:209], v[128:131], v[8:11]
	v_mfma_f32_16x16x32_bf16 v[64:67], v[214:217], v[120:123], v[64:67]
	v_mfma_f32_16x16x32_bf16 v[0:3], v[214:217], v[128:131], v[0:3]
	v_mfma_f32_16x16x32_bf16 v[88:91], v[180:183], v[124:127], v[88:91]
	v_mfma_f32_16x16x32_bf16 v[24:27], v[180:183], v[132:135], v[24:27]
	v_mfma_f32_16x16x32_bf16 v[80:83], v[202:205], v[124:127], v[80:83]
	v_mfma_f32_16x16x32_bf16 v[16:19], v[202:205], v[132:135], v[16:19]
	v_mfma_f32_16x16x32_bf16 v[72:75], v[210:213], v[124:127], v[72:75]
	v_mfma_f32_16x16x32_bf16 v[8:11], v[210:213], v[132:135], v[8:11]
	v_mfma_f32_16x16x32_bf16 v[64:67], v[218:221], v[124:127], v[64:67]
	v_mfma_f32_16x16x32_bf16 v[0:3], v[218:221], v[132:135], v[0:3]
	s_setprio 0
	s_barrier
	s_add_i32 s21, 0, 0x18000
	s_add_i32 s22, 0, 0x1c000
	v_add_u32_e32 v116, s21, v188
	v_add_u32_e32 v132, s22, v188
	ds_read_b128 v[100:103], v116
	ds_read_b128 v[104:107], v116 offset:1024
	ds_read_b128 v[112:115], v116 offset:2048
	ds_read_b128 v[116:119], v116 offset:3072
	ds_read_b128 v[120:123], v132
	ds_read_b128 v[124:127], v132 offset:1024
	ds_read_b128 v[128:131], v132 offset:2048
	ds_read_b128 v[132:135], v132 offset:3072
	s_add_u32 s10, s14, 0x3e000
	s_addc_u32 s11, s15, 0
	s_mov_b32 m0, s55
	v_lshl_add_u64 v[230:231], s[10:11], 0, v[160:161]
	ds_read_b128 v[176:179], v195 offset:32768
	ds_read_b128 v[180:183], v195 offset:33792
	ds_read_b128 v[198:201], v195 offset:34816
	ds_read_b128 v[202:205], v195 offset:35840
	ds_read_b128 v[206:209], v195 offset:36864
	ds_read_b128 v[210:213], v195 offset:37888
	ds_read_b128 v[214:217], v195 offset:38912
	ds_read_b128 v[218:221], v195 offset:39936
	global_load_lds_dwordx4 v[230:231], off
	v_lshl_add_u64 v[230:231], s[10:11], 0, v[164:165]
	s_mov_b32 m0, s95
	s_nop 0
	global_load_lds_dwordx4 v[230:231], off
	s_waitcnt vmcnt(8)
	s_waitcnt lgkmcnt(0)
	s_barrier
	s_setprio 1
	s_waitcnt lgkmcnt(0)
	v_mfma_f32_16x16x32_bf16 v[156:159], v[176:179], v[100:103], v[156:159]
	v_mfma_f32_16x16x32_bf16 v[60:63], v[176:179], v[112:115], v[60:63]
	v_mfma_f32_16x16x32_bf16 v[148:151], v[198:201], v[100:103], v[148:151]
	v_mfma_f32_16x16x32_bf16 v[52:55], v[198:201], v[112:115], v[52:55]
	v_mfma_f32_16x16x32_bf16 v[140:143], v[206:209], v[100:103], v[140:143]
	v_mfma_f32_16x16x32_bf16 v[44:47], v[206:209], v[112:115], v[44:47]
	v_mfma_f32_16x16x32_bf16 v[108:111], v[214:217], v[100:103], v[108:111]
	v_mfma_f32_16x16x32_bf16 v[36:39], v[214:217], v[112:115], v[36:39]
	v_mfma_f32_16x16x32_bf16 v[156:159], v[180:183], v[104:107], v[156:159]
	v_mfma_f32_16x16x32_bf16 v[60:63], v[180:183], v[116:119], v[60:63]
	v_mfma_f32_16x16x32_bf16 v[148:151], v[202:205], v[104:107], v[148:151]
	v_mfma_f32_16x16x32_bf16 v[52:55], v[202:205], v[116:119], v[52:55]
	v_mfma_f32_16x16x32_bf16 v[140:143], v[210:213], v[104:107], v[140:143]
	v_mfma_f32_16x16x32_bf16 v[44:47], v[210:213], v[116:119], v[44:47]
	v_mfma_f32_16x16x32_bf16 v[108:111], v[218:221], v[104:107], v[108:111]
	v_mfma_f32_16x16x32_bf16 v[36:39], v[218:221], v[116:119], v[36:39]
	s_setprio 0
	s_setprio 1
	v_mfma_f32_16x16x32_bf16 v[152:155], v[176:179], v[120:123], v[152:155]
	v_mfma_f32_16x16x32_bf16 v[56:59], v[176:179], v[128:131], v[56:59]
	v_mfma_f32_16x16x32_bf16 v[144:147], v[198:201], v[120:123], v[144:147]
	v_mfma_f32_16x16x32_bf16 v[48:51], v[198:201], v[128:131], v[48:51]
	v_mfma_f32_16x16x32_bf16 v[136:139], v[206:209], v[120:123], v[136:139]
	v_mfma_f32_16x16x32_bf16 v[40:43], v[206:209], v[128:131], v[40:43]
	v_mfma_f32_16x16x32_bf16 v[96:99], v[214:217], v[120:123], v[96:99]
	v_mfma_f32_16x16x32_bf16 v[32:35], v[214:217], v[128:131], v[32:35]
	v_mfma_f32_16x16x32_bf16 v[152:155], v[180:183], v[124:127], v[152:155]
	v_mfma_f32_16x16x32_bf16 v[56:59], v[180:183], v[132:135], v[56:59]
	v_mfma_f32_16x16x32_bf16 v[144:147], v[202:205], v[124:127], v[144:147]
	v_mfma_f32_16x16x32_bf16 v[48:51], v[202:205], v[132:135], v[48:51]
	v_mfma_f32_16x16x32_bf16 v[136:139], v[210:213], v[124:127], v[136:139]
	v_mfma_f32_16x16x32_bf16 v[40:43], v[210:213], v[132:135], v[40:43]
	v_mfma_f32_16x16x32_bf16 v[96:99], v[218:221], v[124:127], v[96:99]
	v_mfma_f32_16x16x32_bf16 v[32:35], v[218:221], v[132:135], v[32:35]
	s_setprio 0
	s_barrier
	s_add_i32 s10, s21, s52
	v_lshl_add_u64 v[222:223], v[222:223], 0, s[56:57]
	s_mov_b32 m0, s10
	ds_read_b128 v[176:179], v195 offset:49152
	ds_read_b128 v[180:183], v195 offset:50176
	ds_read_b128 v[198:201], v195 offset:51200
	ds_read_b128 v[202:205], v195 offset:52224
	ds_read_b128 v[206:209], v195 offset:53248
	ds_read_b128 v[210:213], v195 offset:54272
	ds_read_b128 v[214:217], v195 offset:55296
	ds_read_b128 v[218:221], v195 offset:56320
	global_load_lds_dwordx4 v[222:223], off
	s_add_i32 m0, s10, 0x2000
	s_add_u32 s10, s12, 0x580080
	v_lshl_add_u64 v[222:223], v[224:225], 0, s[56:57]
	s_addc_u32 s11, s13, 0
	s_add_i32 s12, s22, s52
	global_load_lds_dwordx4 v[222:223], off
	v_lshl_add_u64 v[222:223], s[10:11], 0, v[162:163]
	s_mov_b32 m0, s12
	s_nop 0
	global_load_lds_dwordx4 v[222:223], off
	v_lshl_add_u64 v[222:223], s[10:11], 0, v[166:167]
	s_add_i32 m0, s12, 0x2000
	s_nop 0
	global_load_lds_dwordx4 v[222:223], off
	v_lshl_add_u64 v[222:223], v[226:227], 0, s[56:57]
	s_mov_b32 m0, s89
	s_nop 0
	global_load_lds_dwordx4 v[222:223], off
	v_lshl_add_u64 v[222:223], v[228:229], 0, s[56:57]
	s_mov_b32 m0, s90
	s_nop 0
	global_load_lds_dwordx4 v[222:223], off
	s_waitcnt vmcnt(8)
	s_waitcnt lgkmcnt(0)
	s_cmp_lt_u32 s20, 12
	s_cbranch_scc1 .Lffn_wskip
	v_and_b32_e32 v252, 12, v187
	v_lshlrev_b32_e32 v252, 1, v252
	v_and_b32_e32 v253, 0x60, v192
	v_lshl_or_b32 v253, s0, 7, v253
	v_and_b32_e32 v255, 3, v187
	v_or3_b32 v253, v253, v252, v255
	v_lshlrev_b32_e32 v253, 2, v253
	v_readlane_b32 s12, v254, 22
	v_readlane_b32 s13, v254, 23
	v_readlane_b32 s22, v254, 24
	v_readlane_b32 s23, v254, 25
	s_nop 4
	global_load_dword v232, v253, s[70:71]
	global_load_dword v233, v253, s[66:67]
	global_load_dword v234, v253, s[12:13]
	global_load_dword v235, v253, s[22:23]
	global_load_dword v236, v253, s[72:73]
	global_load_dword v237, v253, s[68:69]
	global_load_dword v238, v253, s[62:63]
	global_load_dword v239, v253, s[76:77]
	global_load_dword v240, v253, s[70:71] offset:16
	global_load_dword v241, v253, s[66:67] offset:16
	global_load_dword v242, v253, s[12:13] offset:16
	global_load_dword v243, v253, s[22:23] offset:16
	global_load_dword v196, v253, s[72:73] offset:16
	global_load_dword v197, v253, s[68:69] offset:16
	global_load_dword v189, v253, s[62:63] offset:16
	global_load_dword v190, v253, s[76:77] offset:16
.Lffn_wskip:
	s_barrier
	s_setprio 1
	s_waitcnt lgkmcnt(0)
	v_mfma_f32_16x16x32_bf16 v[92:95], v[176:179], v[100:103], v[92:95]
	v_mfma_f32_16x16x32_bf16 v[28:31], v[176:179], v[112:115], v[28:31]
	v_mfma_f32_16x16x32_bf16 v[84:87], v[198:201], v[100:103], v[84:87]
	v_mfma_f32_16x16x32_bf16 v[20:23], v[198:201], v[112:115], v[20:23]
	v_mfma_f32_16x16x32_bf16 v[76:79], v[206:209], v[100:103], v[76:79]
	v_mfma_f32_16x16x32_bf16 v[12:15], v[206:209], v[112:115], v[12:15]
	v_mfma_f32_16x16x32_bf16 v[68:71], v[214:217], v[100:103], v[68:71]
	v_mfma_f32_16x16x32_bf16 v[4:7], v[214:217], v[112:115], v[4:7]
	v_mfma_f32_16x16x32_bf16 v[92:95], v[180:183], v[104:107], v[92:95]
	v_mfma_f32_16x16x32_bf16 v[28:31], v[180:183], v[116:119], v[28:31]
	v_mfma_f32_16x16x32_bf16 v[84:87], v[202:205], v[104:107], v[84:87]
	v_mfma_f32_16x16x32_bf16 v[20:23], v[202:205], v[116:119], v[20:23]
	v_mfma_f32_16x16x32_bf16 v[76:79], v[210:213], v[104:107], v[76:79]
	v_mfma_f32_16x16x32_bf16 v[12:15], v[210:213], v[116:119], v[12:15]
	v_mfma_f32_16x16x32_bf16 v[68:71], v[218:221], v[104:107], v[68:71]
	v_mfma_f32_16x16x32_bf16 v[4:7], v[218:221], v[116:119], v[4:7]
	s_setprio 0
	s_setprio 1
	v_mfma_f32_16x16x32_bf16 v[88:91], v[176:179], v[120:123], v[88:91]
	v_mfma_f32_16x16x32_bf16 v[24:27], v[176:179], v[128:131], v[24:27]
	v_mfma_f32_16x16x32_bf16 v[80:83], v[198:201], v[120:123], v[80:83]
	v_mfma_f32_16x16x32_bf16 v[16:19], v[198:201], v[128:131], v[16:19]
	v_mfma_f32_16x16x32_bf16 v[72:75], v[206:209], v[120:123], v[72:75]
	v_mfma_f32_16x16x32_bf16 v[8:11], v[206:209], v[128:131], v[8:11]
	v_mfma_f32_16x16x32_bf16 v[64:67], v[214:217], v[120:123], v[64:67]
	v_mfma_f32_16x16x32_bf16 v[0:3], v[214:217], v[128:131], v[0:3]
	v_mfma_f32_16x16x32_bf16 v[88:91], v[180:183], v[124:127], v[88:91]
	v_mfma_f32_16x16x32_bf16 v[24:27], v[180:183], v[132:135], v[24:27]
	v_mfma_f32_16x16x32_bf16 v[80:83], v[202:205], v[124:127], v[80:83]
	v_mfma_f32_16x16x32_bf16 v[16:19], v[202:205], v[132:135], v[16:19]
	v_mfma_f32_16x16x32_bf16 v[72:75], v[210:213], v[124:127], v[72:75]
	v_mfma_f32_16x16x32_bf16 v[8:11], v[210:213], v[132:135], v[8:11]
	v_mfma_f32_16x16x32_bf16 v[64:67], v[218:221], v[124:127], v[64:67]
	v_mfma_f32_16x16x32_bf16 v[0:3], v[218:221], v[132:135], v[0:3]
	s_setprio 0
	s_barrier
	s_add_i32 s20, s20, 2
	s_add_u32 s18, s18, 0x100
	s_addc_u32 s19, s19, 0
	s_cmp_gt_u32 s20, 13
	s_mov_b64 s[10:11], s[8:9]
	s_cbranch_scc0 .LBB0_584
	v_readlane_b32 s8, v254, 2
	v_readlane_b32 s9, v254, 3
	s_and_b64 vcc, exec, s[8:9]
	s_cbranch_vccz .LBB0_587
	s_barrier
.LBB0_587:
	v_readlane_b32 s12, v254, 22
	v_readlane_b32 s13, v254, 23
	v_readlane_b32 s22, v254, 24
	v_readlane_b32 s23, v254, 25
	v_readlane_b32 s15, v254, 44
	v_and_b32_e32 v244, 12, v187
	v_lshlrev_b32_e32 v244, 1, v244
	v_and_b32_e32 v245, 0x60, v192
	v_lshl_or_b32 v245, s0, 7, v245
	v_or_b32_e32 v250, v245, v244
	v_and_b32_e32 v253, 3, v187
	v_or3_b32 v245, v245, v244, v253
	v_lshlrev_b32_e32 v245, 2, v245
	s_mul_hi_i32 s0, s16, 0x78787879
	s_lshr_b32 s1, s0, 31
	s_ashr_i32 s0, s0, 3
	s_add_i32 s0, s0, s1
	s_mul_i32 s1, s0, 17
	s_sub_i32 s1, s16, s1
	s_mul_i32 s14, s1, 0xf8
	s_add_i32 s14, s14, s15
	s_lshl_b32 s8, s0, 12
	s_add_i32 s8, s8, s14
	v_bfe_u32 v244, v186, 4, 2
	v_lshl_or_b32 v244, v244, 2, v253
	v_cmp_lt_u32_e64 s[36:37], 1, v244
	v_add_u32_e32 v251, s14, v244
	v_add_u32_e32 v244, s8, v244
	v_lshlrev_b32_e32 v250, 1, v250
	v_mad_u32_u24 v250, v244, s74, v250
	v_add_u32_e32 v252, 48, v184
	v_and_b32_e32 v252, 63, v252
	v_lshlrev_b32_e32 v252, 2, v252
	v_and_b32_e32 v244, 1, v184
	v_cmp_eq_u32_e32 vcc, 1, v244
	v_mov_b32_e32 v253, 0x5040100
	v_mov_b32_e32 v244, 0x3020706
	s_nop 0
	v_cndmask_b32_e32 v253, v253, v244, vcc
	s_mov_b32 s28, 0
	s_mov_b32 s29, 0xffff0000
	s_mov_b32 s30, 0xcccccccc
	s_mov_b32 s31, 0xcccccccc
	s_mov_b32 s34, 0xffff
	s_mov_b32 s35, 0
	v_mov_b32_e32 v246, 0xc0135761
	v_mov_b32_e32 v247, 0xc0135761
	v_mov_b32_e32 v248, 0xbdd2d3e8
	v_mov_b32_e32 v249, 0xbdd2d3e8
	s_cmp_lg_u32 s14, 0
	s_cbranch_scc1 .Lffn_nz
	v_cndmask_b32_e64 v156, v156, 0, s[34:35]
	v_cndmask_b32_e64 v157, v157, 0, s[34:35]
	v_cndmask_b32_e64 v152, v152, 0, s[34:35]
	v_cndmask_b32_e64 v153, v153, 0, s[34:35]
	v_cndmask_b32_e64 v60, v60, 0, s[34:35]
	v_cndmask_b32_e64 v61, v61, 0, s[34:35]
	v_cndmask_b32_e64 v56, v56, 0, s[34:35]
	v_cndmask_b32_e64 v57, v57, 0, s[34:35]
	s_nop 1
.Lffn_nz:
	s_waitcnt vmcnt(0)
	v_mov_b32_e32 v112, v232
	v_mov_b32_e32 v113, v233
	v_mov_b32_e32 v114, v234
	v_mov_b32_e32 v116, v235
	v_mov_b32_e32 v118, v236
	v_mov_b32_e32 v119, v237
	v_mov_b32_e32 v120, v238
	v_mov_b32_e32 v122, v239
	v_mov_b32_e32 v124, v240
	v_mov_b32_e32 v125, v241
	v_mov_b32_e32 v126, v242
	v_mov_b32_e32 v128, v243
	v_mov_b32_e32 v130, v196
	v_mov_b32_e32 v131, v197
	v_mov_b32_e32 v132, v189
	v_mov_b32_e32 v134, v190
	ds_bpermute_b32 v200, v252, v158
	ds_bpermute_b32 v201, v252, v159
	ds_bpermute_b32 v202, v252, v154
	ds_bpermute_b32 v203, v252, v155
	s_waitcnt lgkmcnt(0)
	ds_bpermute_b32 v204, v252, v62
	ds_bpermute_b32 v205, v252, v63
	ds_bpermute_b32 v206, v252, v58
	ds_bpermute_b32 v207, v252, v59
	v_pk_fma_f32 v[230:231], v[156:157], v[112:113], v[116:117] op_sel_hi:[1,0,0]
	v_pk_fma_f32 v[232:233], v[158:159], v[112:113], v[116:117] op_sel_hi:[1,0,0]
	v_fmac_f32_e32 v230, v201, v113
	v_fmac_f32_e32 v231, v156, v113
	v_fmac_f32_e32 v232, v157, v113
	v_fmac_f32_e32 v233, v158, v113
	v_pk_fma_f32 v[230:231], v[200:201], v[114:115], v[230:231] op_sel_hi:[1,0,1]
	v_pk_fma_f32 v[232:233], v[156:157], v[114:115], v[232:233] op_sel_hi:[1,0,1]
	v_pk_fma_f32 v[234:235], v[152:153], v[118:119], v[122:123] op_sel_hi:[1,0,0]
	v_pk_fma_f32 v[236:237], v[154:155], v[118:119], v[122:123] op_sel_hi:[1,0,0]
	v_fmac_f32_e32 v234, v203, v119
	v_fmac_f32_e32 v235, v152, v119
	v_fmac_f32_e32 v236, v153, v119
	v_fmac_f32_e32 v237, v154, v119
	v_pk_fma_f32 v[234:235], v[202:203], v[120:121], v[234:235] op_sel_hi:[1,0,1]
	v_pk_fma_f32 v[236:237], v[152:153], v[120:121], v[236:237] op_sel_hi:[1,0,1]
	v_pk_mul_f32 v[238:239], v[230:231], v[230:231]
	v_pk_mul_f32 v[240:241], v[232:233], v[232:233]
	v_pk_fma_f32 v[238:239], v[238:239], v[248:249], v[246:247]
	v_pk_fma_f32 v[240:241], v[240:241], v[248:249], v[246:247]
	v_pk_mul_f32 v[238:239], v[230:231], v[238:239]
	v_pk_mul_f32 v[240:241], v[232:233], v[240:241]
	v_exp_f32_e32 v238, v238
	v_exp_f32_e32 v239, v239
	v_exp_f32_e32 v240, v240
	v_exp_f32_e32 v241, v241
	v_pk_add_f32 v[238:239], v[238:239], 1.0 op_sel_hi:[1,0]
	v_pk_add_f32 v[240:241], v[240:241], 1.0 op_sel_hi:[1,0]
	v_rcp_f32_e32 v238, v238
	v_rcp_f32_e32 v239, v239
	v_rcp_f32_e32 v240, v240
	v_rcp_f32_e32 v241, v241
	v_pk_mul_f32 v[230:231], v[230:231], v[234:235]
	v_pk_mul_f32 v[232:233], v[232:233], v[236:237]
	v_pk_mul_f32 v[238:239], v[230:231], v[238:239]
	v_pk_mul_f32 v[240:241], v[232:233], v[240:241]
	v_cvt_pk_bf16_f32 v212, v238, v239
	v_cvt_pk_bf16_f32 v213, v240, v241
	s_mov_b64 vcc, s[30:31]
	s_nop 0
	v_mov_b32_dpp v214, v212 quad_perm:[1,0,3,2] row_mask:0xf bank_mask:0xf
	v_mov_b32_dpp v215, v213 quad_perm:[1,0,3,2] row_mask:0xf bank_mask:0xf
	v_perm_b32 v216, v214, v212, v253
	v_perm_b32 v217, v215, v213, v253
	s_nop 1
	v_mov_b32_dpp v218, v216 quad_perm:[2,3,0,1] row_mask:0xf bank_mask:0xf
	v_mov_b32_dpp v219, v217 quad_perm:[2,3,0,1] row_mask:0xf bank_mask:0xf
	v_cndmask_b32_e32 v176, v216, v219, vcc
	v_cndmask_b32_e32 v177, v218, v217, vcc
	s_waitcnt lgkmcnt(0)
	s_mov_b64 vcc, s[28:29]
	v_cndmask_b32_e32 v208, v150, v158, vcc
	v_cndmask_b32_e32 v209, v151, v159, vcc
	v_cndmask_b32_e32 v210, v146, v154, vcc
	v_cndmask_b32_e32 v211, v147, v155, vcc
	ds_bpermute_b32 v200, v252, v208
	ds_bpermute_b32 v201, v252, v209
	ds_bpermute_b32 v202, v252, v210
	ds_bpermute_b32 v203, v252, v211
	v_pk_fma_f32 v[230:231], v[60:61], v[124:125], v[128:129] op_sel_hi:[1,0,0]
	v_pk_fma_f32 v[232:233], v[62:63], v[124:125], v[128:129] op_sel_hi:[1,0,0]
	v_fmac_f32_e32 v230, v205, v125
	v_fmac_f32_e32 v231, v60, v125
	v_fmac_f32_e32 v232, v61, v125
	v_fmac_f32_e32 v233, v62, v125
	v_pk_fma_f32 v[230:231], v[204:205], v[126:127], v[230:231] op_sel_hi:[1,0,1]
	v_pk_fma_f32 v[232:233], v[60:61], v[126:127], v[232:233] op_sel_hi:[1,0,1]
	v_pk_fma_f32 v[234:235], v[56:57], v[130:131], v[134:135] op_sel_hi:[1,0,0]
	v_pk_fma_f32 v[236:237], v[58:59], v[130:131], v[134:135] op_sel_hi:[1,0,0]
	v_fmac_f32_e32 v234, v207, v131
	v_fmac_f32_e32 v235, v56, v131
	v_fmac_f32_e32 v236, v57, v131
	v_fmac_f32_e32 v237, v58, v131
	v_pk_fma_f32 v[234:235], v[206:207], v[132:133], v[234:235] op_sel_hi:[1,0,1]
	v_pk_fma_f32 v[236:237], v[56:57], v[132:133], v[236:237] op_sel_hi:[1,0,1]
	v_pk_mul_f32 v[238:239], v[230:231], v[230:231]
	v_pk_mul_f32 v[240:241], v[232:233], v[232:233]
	v_pk_fma_f32 v[238:239], v[238:239], v[248:249], v[246:247]
	v_pk_fma_f32 v[240:241], v[240:241], v[248:249], v[246:247]
	v_pk_mul_f32 v[238:239], v[230:231], v[238:239]
	v_pk_mul_f32 v[240:241], v[232:233], v[240:241]
	v_exp_f32_e32 v238, v238
	v_exp_f32_e32 v239, v239
	v_exp_f32_e32 v240, v240
	v_exp_f32_e32 v241, v241
	v_pk_add_f32 v[238:239], v[238:239], 1.0 op_sel_hi:[1,0]
	v_pk_add_f32 v[240:241], v[240:241], 1.0 op_sel_hi:[1,0]
	v_rcp_f32_e32 v238, v238
	v_rcp_f32_e32 v239, v239
	v_rcp_f32_e32 v240, v240
	v_rcp_f32_e32 v241, v241
	v_pk_mul_f32 v[230:231], v[230:231], v[234:235]
	v_pk_mul_f32 v[232:233], v[232:233], v[236:237]
	v_pk_mul_f32 v[238:239], v[230:231], v[238:239]
	v_pk_mul_f32 v[240:241], v[232:233], v[240:241]
	v_cvt_pk_bf16_f32 v212, v238, v239
	v_cvt_pk_bf16_f32 v213, v240, v241
	s_mov_b64 vcc, s[30:31]
	s_nop 0
	v_mov_b32_dpp v214, v212 quad_perm:[1,0,3,2] row_mask:0xf bank_mask:0xf
	v_mov_b32_dpp v215, v213 quad_perm:[1,0,3,2] row_mask:0xf bank_mask:0xf
	v_perm_b32 v216, v214, v212, v253
	v_perm_b32 v217, v215, v213, v253
	s_nop 1
	v_mov_b32_dpp v218, v216 quad_perm:[2,3,0,1] row_mask:0xf bank_mask:0xf
	v_mov_b32_dpp v219, v217 quad_perm:[2,3,0,1] row_mask:0xf bank_mask:0xf
	v_cndmask_b32_e32 v178, v216, v219, vcc
	v_cndmask_b32_e32 v179, v218, v217, vcc
	s_movk_i32 s15, 0x1002
	v_cmp_gt_i32_e64 s[24:25], s15, v251
	s_sub_u32 s84, s58, 0x2c00
	s_subb_u32 s85, s59, 0
	s_and_b64 s[24:25], s[24:25], s[36:37]
	s_mov_b64 exec, s[24:25]
	global_store_dwordx4 v250, v[176:179], s[84:85] nt
	s_mov_b64 exec, -1
	s_nop 0
	s_waitcnt lgkmcnt(0)
	s_mov_b64 vcc, s[28:29]
	v_cndmask_b32_e32 v208, v54, v62, vcc
	v_cndmask_b32_e32 v209, v55, v63, vcc
	v_cndmask_b32_e32 v210, v50, v58, vcc
	v_cndmask_b32_e32 v211, v51, v59, vcc
	ds_bpermute_b32 v204, v252, v208
	ds_bpermute_b32 v205, v252, v209
	ds_bpermute_b32 v206, v252, v210
	ds_bpermute_b32 v207, v252, v211
	v_pk_fma_f32 v[230:231], v[148:149], v[112:113], v[116:117] op_sel_hi:[1,0,0]
	v_pk_fma_f32 v[232:233], v[150:151], v[112:113], v[116:117] op_sel_hi:[1,0,0]
	v_fmac_f32_e32 v230, v201, v113
	v_fmac_f32_e32 v231, v148, v113
	v_fmac_f32_e32 v232, v149, v113
	v_fmac_f32_e32 v233, v150, v113
	v_pk_fma_f32 v[230:231], v[200:201], v[114:115], v[230:231] op_sel_hi:[1,0,1]
	v_pk_fma_f32 v[232:233], v[148:149], v[114:115], v[232:233] op_sel_hi:[1,0,1]
	v_pk_fma_f32 v[234:235], v[144:145], v[118:119], v[122:123] op_sel_hi:[1,0,0]
	v_pk_fma_f32 v[236:237], v[146:147], v[118:119], v[122:123] op_sel_hi:[1,0,0]
	v_fmac_f32_e32 v234, v203, v119
	v_fmac_f32_e32 v235, v144, v119
	v_fmac_f32_e32 v236, v145, v119
	v_fmac_f32_e32 v237, v146, v119
	v_pk_fma_f32 v[234:235], v[202:203], v[120:121], v[234:235] op_sel_hi:[1,0,1]
	v_pk_fma_f32 v[236:237], v[144:145], v[120:121], v[236:237] op_sel_hi:[1,0,1]
	v_pk_mul_f32 v[238:239], v[230:231], v[230:231]
	v_pk_mul_f32 v[240:241], v[232:233], v[232:233]
	v_pk_fma_f32 v[238:239], v[238:239], v[248:249], v[246:247]
	v_pk_fma_f32 v[240:241], v[240:241], v[248:249], v[246:247]
	v_pk_mul_f32 v[238:239], v[230:231], v[238:239]
	v_pk_mul_f32 v[240:241], v[232:233], v[240:241]
	v_exp_f32_e32 v238, v238
	v_exp_f32_e32 v239, v239
	v_exp_f32_e32 v240, v240
	v_exp_f32_e32 v241, v241
	v_pk_add_f32 v[238:239], v[238:239], 1.0 op_sel_hi:[1,0]
	v_pk_add_f32 v[240:241], v[240:241], 1.0 op_sel_hi:[1,0]
	v_rcp_f32_e32 v238, v238
	v_rcp_f32_e32 v239, v239
	v_rcp_f32_e32 v240, v240
	v_rcp_f32_e32 v241, v241
	v_pk_mul_f32 v[230:231], v[230:231], v[234:235]
	v_pk_mul_f32 v[232:233], v[232:233], v[236:237]
	v_pk_mul_f32 v[238:239], v[230:231], v[238:239]
	v_pk_mul_f32 v[240:241], v[232:233], v[240:241]
	v_cvt_pk_bf16_f32 v212, v238, v239
	v_cvt_pk_bf16_f32 v213, v240, v241
	s_mov_b64 vcc, s[30:31]
	s_nop 0
	v_mov_b32_dpp v214, v212 quad_perm:[1,0,3,2] row_mask:0xf bank_mask:0xf
	v_mov_b32_dpp v215, v213 quad_perm:[1,0,3,2] row_mask:0xf bank_mask:0xf
	v_perm_b32 v216, v214, v212, v253
	v_perm_b32 v217, v215, v213, v253
	s_nop 1
	v_mov_b32_dpp v218, v216 quad_perm:[2,3,0,1] row_mask:0xf bank_mask:0xf
	v_mov_b32_dpp v219, v217 quad_perm:[2,3,0,1] row_mask:0xf bank_mask:0xf
	v_cndmask_b32_e32 v180, v216, v219, vcc
	v_cndmask_b32_e32 v181, v218, v217, vcc
	s_waitcnt lgkmcnt(0)
	s_mov_b64 vcc, s[28:29]
	v_cndmask_b32_e32 v208, v142, v150, vcc
	v_cndmask_b32_e32 v209, v143, v151, vcc
	v_cndmask_b32_e32 v210, v138, v146, vcc
	v_cndmask_b32_e32 v211, v139, v147, vcc
	ds_bpermute_b32 v200, v252, v208
	ds_bpermute_b32 v201, v252, v209
	ds_bpermute_b32 v202, v252, v210
	ds_bpermute_b32 v203, v252, v211
	v_pk_fma_f32 v[230:231], v[52:53], v[124:125], v[128:129] op_sel_hi:[1,0,0]
	v_pk_fma_f32 v[232:233], v[54:55], v[124:125], v[128:129] op_sel_hi:[1,0,0]
	v_fmac_f32_e32 v230, v205, v125
	v_fmac_f32_e32 v231, v52, v125
	v_fmac_f32_e32 v232, v53, v125
	v_fmac_f32_e32 v233, v54, v125
	v_pk_fma_f32 v[230:231], v[204:205], v[126:127], v[230:231] op_sel_hi:[1,0,1]
	v_pk_fma_f32 v[232:233], v[52:53], v[126:127], v[232:233] op_sel_hi:[1,0,1]
	v_pk_fma_f32 v[234:235], v[48:49], v[130:131], v[134:135] op_sel_hi:[1,0,0]
	v_pk_fma_f32 v[236:237], v[50:51], v[130:131], v[134:135] op_sel_hi:[1,0,0]
	v_fmac_f32_e32 v234, v207, v131
	v_fmac_f32_e32 v235, v48, v131
	v_fmac_f32_e32 v236, v49, v131
	v_fmac_f32_e32 v237, v50, v131
	v_pk_fma_f32 v[234:235], v[206:207], v[132:133], v[234:235] op_sel_hi:[1,0,1]
	v_pk_fma_f32 v[236:237], v[48:49], v[132:133], v[236:237] op_sel_hi:[1,0,1]
	v_pk_mul_f32 v[238:239], v[230:231], v[230:231]
	v_pk_mul_f32 v[240:241], v[232:233], v[232:233]
	v_pk_fma_f32 v[238:239], v[238:239], v[248:249], v[246:247]
	v_pk_fma_f32 v[240:241], v[240:241], v[248:249], v[246:247]
	v_pk_mul_f32 v[238:239], v[230:231], v[238:239]
	v_pk_mul_f32 v[240:241], v[232:233], v[240:241]
	v_exp_f32_e32 v238, v238
	v_exp_f32_e32 v239, v239
	v_exp_f32_e32 v240, v240
	v_exp_f32_e32 v241, v241
	v_pk_add_f32 v[238:239], v[238:239], 1.0 op_sel_hi:[1,0]
	v_pk_add_f32 v[240:241], v[240:241], 1.0 op_sel_hi:[1,0]
	v_rcp_f32_e32 v238, v238
	v_rcp_f32_e32 v239, v239
	v_rcp_f32_e32 v240, v240
	v_rcp_f32_e32 v241, v241
	v_pk_mul_f32 v[230:231], v[230:231], v[234:235]
	v_pk_mul_f32 v[232:233], v[232:233], v[236:237]
	v_pk_mul_f32 v[238:239], v[230:231], v[238:239]
	v_pk_mul_f32 v[240:241], v[232:233], v[240:241]
	v_cvt_pk_bf16_f32 v212, v238, v239
	v_cvt_pk_bf16_f32 v213, v240, v241
	s_mov_b64 vcc, s[30:31]
	s_nop 0
	v_mov_b32_dpp v214, v212 quad_perm:[1,0,3,2] row_mask:0xf bank_mask:0xf
	v_mov_b32_dpp v215, v213 quad_perm:[1,0,3,2] row_mask:0xf bank_mask:0xf
	v_perm_b32 v216, v214, v212, v253
	v_perm_b32 v217, v215, v213, v253
	s_nop 1
	v_mov_b32_dpp v218, v216 quad_perm:[2,3,0,1] row_mask:0xf bank_mask:0xf
	v_mov_b32_dpp v219, v217 quad_perm:[2,3,0,1] row_mask:0xf bank_mask:0xf
	v_cndmask_b32_e32 v182, v216, v219, vcc
	v_cndmask_b32_e32 v183, v218, v217, vcc
	s_movk_i32 s15, 0xff2
	v_cmp_gt_i32_e64 s[24:25], s15, v251
	s_add_u32 s84, s58, 0x13400
	s_addc_u32 s85, s59, 0
	s_mov_b64 exec, s[24:25]
	global_store_dwordx4 v250, v[180:183], s[84:85] nt
	s_mov_b64 exec, -1
	s_nop 0
	s_waitcnt lgkmcnt(0)
	s_mov_b64 vcc, s[28:29]
	v_cndmask_b32_e32 v208, v46, v54, vcc
	v_cndmask_b32_e32 v209, v47, v55, vcc
	v_cndmask_b32_e32 v210, v42, v50, vcc
	v_cndmask_b32_e32 v211, v43, v51, vcc
	ds_bpermute_b32 v204, v252, v208
	ds_bpermute_b32 v205, v252, v209
	ds_bpermute_b32 v206, v252, v210
	ds_bpermute_b32 v207, v252, v211
	v_pk_fma_f32 v[230:231], v[140:141], v[112:113], v[116:117] op_sel_hi:[1,0,0]
	v_pk_fma_f32 v[232:233], v[142:143], v[112:113], v[116:117] op_sel_hi:[1,0,0]
	v_fmac_f32_e32 v230, v201, v113
	v_fmac_f32_e32 v231, v140, v113
	v_fmac_f32_e32 v232, v141, v113
	v_fmac_f32_e32 v233, v142, v113
	v_pk_fma_f32 v[230:231], v[200:201], v[114:115], v[230:231] op_sel_hi:[1,0,1]
	v_pk_fma_f32 v[232:233], v[140:141], v[114:115], v[232:233] op_sel_hi:[1,0,1]
	v_pk_fma_f32 v[234:235], v[136:137], v[118:119], v[122:123] op_sel_hi:[1,0,0]
	v_pk_fma_f32 v[236:237], v[138:139], v[118:119], v[122:123] op_sel_hi:[1,0,0]
	v_fmac_f32_e32 v234, v203, v119
	v_fmac_f32_e32 v235, v136, v119
	v_fmac_f32_e32 v236, v137, v119
	v_fmac_f32_e32 v237, v138, v119
	v_pk_fma_f32 v[234:235], v[202:203], v[120:121], v[234:235] op_sel_hi:[1,0,1]
	v_pk_fma_f32 v[236:237], v[136:137], v[120:121], v[236:237] op_sel_hi:[1,0,1]
	v_pk_mul_f32 v[238:239], v[230:231], v[230:231]
	v_pk_mul_f32 v[240:241], v[232:233], v[232:233]
	v_pk_fma_f32 v[238:239], v[238:239], v[248:249], v[246:247]
	v_pk_fma_f32 v[240:241], v[240:241], v[248:249], v[246:247]
	v_pk_mul_f32 v[238:239], v[230:231], v[238:239]
	v_pk_mul_f32 v[240:241], v[232:233], v[240:241]
	v_exp_f32_e32 v238, v238
	v_exp_f32_e32 v239, v239
	v_exp_f32_e32 v240, v240
	v_exp_f32_e32 v241, v241
	v_pk_add_f32 v[238:239], v[238:239], 1.0 op_sel_hi:[1,0]
	v_pk_add_f32 v[240:241], v[240:241], 1.0 op_sel_hi:[1,0]
	v_rcp_f32_e32 v238, v238
	v_rcp_f32_e32 v239, v239
	v_rcp_f32_e32 v240, v240
	v_rcp_f32_e32 v241, v241
	v_pk_mul_f32 v[230:231], v[230:231], v[234:235]
	v_pk_mul_f32 v[232:233], v[232:233], v[236:237]
	v_pk_mul_f32 v[238:239], v[230:231], v[238:239]
	v_pk_mul_f32 v[240:241], v[232:233], v[240:241]
	v_cvt_pk_bf16_f32 v212, v238, v239
	v_cvt_pk_bf16_f32 v213, v240, v241
	s_mov_b64 vcc, s[30:31]
	s_nop 0
	v_mov_b32_dpp v214, v212 quad_perm:[1,0,3,2] row_mask:0xf bank_mask:0xf
	v_mov_b32_dpp v215, v213 quad_perm:[1,0,3,2] row_mask:0xf bank_mask:0xf
	v_perm_b32 v216, v214, v212, v253
	v_perm_b32 v217, v215, v213, v253
	s_nop 1
	v_mov_b32_dpp v218, v216 quad_perm:[2,3,0,1] row_mask:0xf bank_mask:0xf
	v_mov_b32_dpp v219, v217 quad_perm:[2,3,0,1] row_mask:0xf bank_mask:0xf
	v_cndmask_b32_e32 v176, v216, v219, vcc
	v_cndmask_b32_e32 v177, v218, v217, vcc
	s_waitcnt lgkmcnt(0)
	s_mov_b64 vcc, s[28:29]
	v_cndmask_b32_e32 v208, v110, v142, vcc
	v_cndmask_b32_e32 v209, v111, v143, vcc
	v_cndmask_b32_e32 v210, v98, v138, vcc
	v_cndmask_b32_e32 v211, v99, v139, vcc
	ds_bpermute_b32 v200, v252, v208
	ds_bpermute_b32 v201, v252, v209
	ds_bpermute_b32 v202, v252, v210
	ds_bpermute_b32 v203, v252, v211
	v_pk_fma_f32 v[230:231], v[44:45], v[124:125], v[128:129] op_sel_hi:[1,0,0]
	v_pk_fma_f32 v[232:233], v[46:47], v[124:125], v[128:129] op_sel_hi:[1,0,0]
	v_fmac_f32_e32 v230, v205, v125
	v_fmac_f32_e32 v231, v44, v125
	v_fmac_f32_e32 v232, v45, v125
	v_fmac_f32_e32 v233, v46, v125
	v_pk_fma_f32 v[230:231], v[204:205], v[126:127], v[230:231] op_sel_hi:[1,0,1]
	v_pk_fma_f32 v[232:233], v[44:45], v[126:127], v[232:233] op_sel_hi:[1,0,1]
	v_pk_fma_f32 v[234:235], v[40:41], v[130:131], v[134:135] op_sel_hi:[1,0,0]
	v_pk_fma_f32 v[236:237], v[42:43], v[130:131], v[134:135] op_sel_hi:[1,0,0]
	v_fmac_f32_e32 v234, v207, v131
	v_fmac_f32_e32 v235, v40, v131
	v_fmac_f32_e32 v236, v41, v131
	v_fmac_f32_e32 v237, v42, v131
	v_pk_fma_f32 v[234:235], v[206:207], v[132:133], v[234:235] op_sel_hi:[1,0,1]
	v_pk_fma_f32 v[236:237], v[40:41], v[132:133], v[236:237] op_sel_hi:[1,0,1]
	v_pk_mul_f32 v[238:239], v[230:231], v[230:231]
	v_pk_mul_f32 v[240:241], v[232:233], v[232:233]
	v_pk_fma_f32 v[238:239], v[238:239], v[248:249], v[246:247]
	v_pk_fma_f32 v[240:241], v[240:241], v[248:249], v[246:247]
	v_pk_mul_f32 v[238:239], v[230:231], v[238:239]
	v_pk_mul_f32 v[240:241], v[232:233], v[240:241]
	v_exp_f32_e32 v238, v238
	v_exp_f32_e32 v239, v239
	v_exp_f32_e32 v240, v240
	v_exp_f32_e32 v241, v241
	v_pk_add_f32 v[238:239], v[238:239], 1.0 op_sel_hi:[1,0]
	v_pk_add_f32 v[240:241], v[240:241], 1.0 op_sel_hi:[1,0]
	v_rcp_f32_e32 v238, v238
	v_rcp_f32_e32 v239, v239
	v_rcp_f32_e32 v240, v240
	v_rcp_f32_e32 v241, v241
	v_pk_mul_f32 v[230:231], v[230:231], v[234:235]
	v_pk_mul_f32 v[232:233], v[232:233], v[236:237]
	v_pk_mul_f32 v[238:239], v[230:231], v[238:239]
	v_pk_mul_f32 v[240:241], v[232:233], v[240:241]
	v_cvt_pk_bf16_f32 v212, v238, v239
	v_cvt_pk_bf16_f32 v213, v240, v241
	s_mov_b64 vcc, s[30:31]
	s_nop 0
	v_mov_b32_dpp v214, v212 quad_perm:[1,0,3,2] row_mask:0xf bank_mask:0xf
	v_mov_b32_dpp v215, v213 quad_perm:[1,0,3,2] row_mask:0xf bank_mask:0xf
	v_perm_b32 v216, v214, v212, v253
	v_perm_b32 v217, v215, v213, v253
	s_nop 1
	v_mov_b32_dpp v218, v216 quad_perm:[2,3,0,1] row_mask:0xf bank_mask:0xf
	v_mov_b32_dpp v219, v217 quad_perm:[2,3,0,1] row_mask:0xf bank_mask:0xf
	v_cndmask_b32_e32 v178, v216, v219, vcc
	v_cndmask_b32_e32 v179, v218, v217, vcc
	s_movk_i32 s15, 0xfe2
	v_cmp_gt_i32_e64 s[24:25], s15, v251
	s_add_u32 s84, s58, 0x29400
	s_addc_u32 s85, s59, 0
	s_mov_b64 exec, s[24:25]
	global_store_dwordx4 v250, v[176:179], s[84:85] nt
	s_mov_b64 exec, -1
	s_nop 0
	s_waitcnt lgkmcnt(0)
	s_mov_b64 vcc, s[28:29]
	v_cndmask_b32_e32 v208, v38, v46, vcc
	v_cndmask_b32_e32 v209, v39, v47, vcc
	v_cndmask_b32_e32 v210, v34, v42, vcc
	v_cndmask_b32_e32 v211, v35, v43, vcc
	ds_bpermute_b32 v204, v252, v208
	ds_bpermute_b32 v205, v252, v209
	ds_bpermute_b32 v206, v252, v210
	ds_bpermute_b32 v207, v252, v211
	v_pk_fma_f32 v[230:231], v[108:109], v[112:113], v[116:117] op_sel_hi:[1,0,0]
	v_pk_fma_f32 v[232:233], v[110:111], v[112:113], v[116:117] op_sel_hi:[1,0,0]
	v_fmac_f32_e32 v230, v201, v113
	v_fmac_f32_e32 v231, v108, v113
	v_fmac_f32_e32 v232, v109, v113
	v_fmac_f32_e32 v233, v110, v113
	v_pk_fma_f32 v[230:231], v[200:201], v[114:115], v[230:231] op_sel_hi:[1,0,1]
	v_pk_fma_f32 v[232:233], v[108:109], v[114:115], v[232:233] op_sel_hi:[1,0,1]
	v_pk_fma_f32 v[234:235], v[96:97], v[118:119], v[122:123] op_sel_hi:[1,0,0]
	v_pk_fma_f32 v[236:237], v[98:99], v[118:119], v[122:123] op_sel_hi:[1,0,0]
	v_fmac_f32_e32 v234, v203, v119
	v_fmac_f32_e32 v235, v96, v119
	v_fmac_f32_e32 v236, v97, v119
	v_fmac_f32_e32 v237, v98, v119
	v_pk_fma_f32 v[234:235], v[202:203], v[120:121], v[234:235] op_sel_hi:[1,0,1]
	v_pk_fma_f32 v[236:237], v[96:97], v[120:121], v[236:237] op_sel_hi:[1,0,1]
	v_pk_mul_f32 v[238:239], v[230:231], v[230:231]
	v_pk_mul_f32 v[240:241], v[232:233], v[232:233]
	v_pk_fma_f32 v[238:239], v[238:239], v[248:249], v[246:247]
	v_pk_fma_f32 v[240:241], v[240:241], v[248:249], v[246:247]
	v_pk_mul_f32 v[238:239], v[230:231], v[238:239]
	v_pk_mul_f32 v[240:241], v[232:233], v[240:241]
	v_exp_f32_e32 v238, v238
	v_exp_f32_e32 v239, v239
	v_exp_f32_e32 v240, v240
	v_exp_f32_e32 v241, v241
	v_pk_add_f32 v[238:239], v[238:239], 1.0 op_sel_hi:[1,0]
	v_pk_add_f32 v[240:241], v[240:241], 1.0 op_sel_hi:[1,0]
	v_rcp_f32_e32 v238, v238
	v_rcp_f32_e32 v239, v239
	v_rcp_f32_e32 v240, v240
	v_rcp_f32_e32 v241, v241
	v_pk_mul_f32 v[230:231], v[230:231], v[234:235]
	v_pk_mul_f32 v[232:233], v[232:233], v[236:237]
	v_pk_mul_f32 v[238:239], v[230:231], v[238:239]
	v_pk_mul_f32 v[240:241], v[232:233], v[240:241]
	v_cvt_pk_bf16_f32 v212, v238, v239
	v_cvt_pk_bf16_f32 v213, v240, v241
	s_mov_b64 vcc, s[30:31]
	s_nop 0
	v_mov_b32_dpp v214, v212 quad_perm:[1,0,3,2] row_mask:0xf bank_mask:0xf
	v_mov_b32_dpp v215, v213 quad_perm:[1,0,3,2] row_mask:0xf bank_mask:0xf
	v_perm_b32 v216, v214, v212, v253
	v_perm_b32 v217, v215, v213, v253
	s_nop 1
	v_mov_b32_dpp v218, v216 quad_perm:[2,3,0,1] row_mask:0xf bank_mask:0xf
	v_mov_b32_dpp v219, v217 quad_perm:[2,3,0,1] row_mask:0xf bank_mask:0xf
	v_cndmask_b32_e32 v180, v216, v219, vcc
	v_cndmask_b32_e32 v181, v218, v217, vcc
	s_waitcnt lgkmcnt(0)
	ds_bpermute_b32 v200, v252, v94
	ds_bpermute_b32 v201, v252, v95
	ds_bpermute_b32 v202, v252, v90
	ds_bpermute_b32 v203, v252, v91
	v_pk_fma_f32 v[230:231], v[36:37], v[124:125], v[128:129] op_sel_hi:[1,0,0]
	v_pk_fma_f32 v[232:233], v[38:39], v[124:125], v[128:129] op_sel_hi:[1,0,0]
	v_fmac_f32_e32 v230, v205, v125
	v_fmac_f32_e32 v231, v36, v125
	v_fmac_f32_e32 v232, v37, v125
	v_fmac_f32_e32 v233, v38, v125
	v_pk_fma_f32 v[230:231], v[204:205], v[126:127], v[230:231] op_sel_hi:[1,0,1]
	v_pk_fma_f32 v[232:233], v[36:37], v[126:127], v[232:233] op_sel_hi:[1,0,1]
	v_pk_fma_f32 v[234:235], v[32:33], v[130:131], v[134:135] op_sel_hi:[1,0,0]
	v_pk_fma_f32 v[236:237], v[34:35], v[130:131], v[134:135] op_sel_hi:[1,0,0]
	v_fmac_f32_e32 v234, v207, v131
	v_fmac_f32_e32 v235, v32, v131
	v_fmac_f32_e32 v236, v33, v131
	v_fmac_f32_e32 v237, v34, v131
	v_pk_fma_f32 v[234:235], v[206:207], v[132:133], v[234:235] op_sel_hi:[1,0,1]
	v_pk_fma_f32 v[236:237], v[32:33], v[132:133], v[236:237] op_sel_hi:[1,0,1]
	v_pk_mul_f32 v[238:239], v[230:231], v[230:231]
	v_pk_mul_f32 v[240:241], v[232:233], v[232:233]
	v_pk_fma_f32 v[238:239], v[238:239], v[248:249], v[246:247]
	v_pk_fma_f32 v[240:241], v[240:241], v[248:249], v[246:247]
	v_pk_mul_f32 v[238:239], v[230:231], v[238:239]
	v_pk_mul_f32 v[240:241], v[232:233], v[240:241]
	v_exp_f32_e32 v238, v238
	v_exp_f32_e32 v239, v239
	v_exp_f32_e32 v240, v240
	v_exp_f32_e32 v241, v241
	v_pk_add_f32 v[238:239], v[238:239], 1.0 op_sel_hi:[1,0]
	v_pk_add_f32 v[240:241], v[240:241], 1.0 op_sel_hi:[1,0]
	v_rcp_f32_e32 v238, v238
	v_rcp_f32_e32 v239, v239
	v_rcp_f32_e32 v240, v240
	v_rcp_f32_e32 v241, v241
	v_pk_mul_f32 v[230:231], v[230:231], v[234:235]
	v_pk_mul_f32 v[232:233], v[232:233], v[236:237]
	v_pk_mul_f32 v[238:239], v[230:231], v[238:239]
	v_pk_mul_f32 v[240:241], v[232:233], v[240:241]
	v_cvt_pk_bf16_f32 v212, v238, v239
	v_cvt_pk_bf16_f32 v213, v240, v241
	s_mov_b64 vcc, s[30:31]
	s_nop 0
	v_mov_b32_dpp v214, v212 quad_perm:[1,0,3,2] row_mask:0xf bank_mask:0xf
	v_mov_b32_dpp v215, v213 quad_perm:[1,0,3,2] row_mask:0xf bank_mask:0xf
	v_perm_b32 v216, v214, v212, v253
	v_perm_b32 v217, v215, v213, v253
	s_nop 1
	v_mov_b32_dpp v218, v216 quad_perm:[2,3,0,1] row_mask:0xf bank_mask:0xf
	v_mov_b32_dpp v219, v217 quad_perm:[2,3,0,1] row_mask:0xf bank_mask:0xf
	v_cndmask_b32_e32 v182, v216, v219, vcc
	v_cndmask_b32_e32 v183, v218, v217, vcc
	s_movk_i32 s15, 0xfd2
	v_cmp_gt_i32_e64 s[24:25], s15, v251
	s_add_u32 s84, s58, 0x3f400
	s_addc_u32 s85, s59, 0
	s_mov_b64 exec, s[24:25]
	global_store_dwordx4 v250, v[180:183], s[84:85] nt
	s_mov_b64 exec, -1
	s_nop 0
	s_waitcnt lgkmcnt(0)
	ds_bpermute_b32 v204, v252, v30
	ds_bpermute_b32 v205, v252, v31
	ds_bpermute_b32 v206, v252, v26
	ds_bpermute_b32 v207, v252, v27
	v_pk_fma_f32 v[230:231], v[92:93], v[112:113], v[116:117] op_sel_hi:[1,0,0]
	v_pk_fma_f32 v[232:233], v[94:95], v[112:113], v[116:117] op_sel_hi:[1,0,0]
	v_fmac_f32_e32 v230, v201, v113
	v_fmac_f32_e32 v231, v92, v113
	v_fmac_f32_e32 v232, v93, v113
	v_fmac_f32_e32 v233, v94, v113
	v_pk_fma_f32 v[230:231], v[200:201], v[114:115], v[230:231] op_sel_hi:[1,0,1]
	v_pk_fma_f32 v[232:233], v[92:93], v[114:115], v[232:233] op_sel_hi:[1,0,1]
	v_pk_fma_f32 v[234:235], v[88:89], v[118:119], v[122:123] op_sel_hi:[1,0,0]
	v_pk_fma_f32 v[236:237], v[90:91], v[118:119], v[122:123] op_sel_hi:[1,0,0]
	v_fmac_f32_e32 v234, v203, v119
	v_fmac_f32_e32 v235, v88, v119
	v_fmac_f32_e32 v236, v89, v119
	v_fmac_f32_e32 v237, v90, v119
	v_pk_fma_f32 v[234:235], v[202:203], v[120:121], v[234:235] op_sel_hi:[1,0,1]
	v_pk_fma_f32 v[236:237], v[88:89], v[120:121], v[236:237] op_sel_hi:[1,0,1]
	v_pk_mul_f32 v[238:239], v[230:231], v[230:231]
	v_pk_mul_f32 v[240:241], v[232:233], v[232:233]
	v_pk_fma_f32 v[238:239], v[238:239], v[248:249], v[246:247]
	v_pk_fma_f32 v[240:241], v[240:241], v[248:249], v[246:247]
	v_pk_mul_f32 v[238:239], v[230:231], v[238:239]
	v_pk_mul_f32 v[240:241], v[232:233], v[240:241]
	v_exp_f32_e32 v238, v238
	v_exp_f32_e32 v239, v239
	v_exp_f32_e32 v240, v240
	v_exp_f32_e32 v241, v241
	v_pk_add_f32 v[238:239], v[238:239], 1.0 op_sel_hi:[1,0]
	v_pk_add_f32 v[240:241], v[240:241], 1.0 op_sel_hi:[1,0]
	v_rcp_f32_e32 v238, v238
	v_rcp_f32_e32 v239, v239
	v_rcp_f32_e32 v240, v240
	v_rcp_f32_e32 v241, v241
	v_pk_mul_f32 v[230:231], v[230:231], v[234:235]
	v_pk_mul_f32 v[232:233], v[232:233], v[236:237]
	v_pk_mul_f32 v[238:239], v[230:231], v[238:239]
	v_pk_mul_f32 v[240:241], v[232:233], v[240:241]
	v_cvt_pk_bf16_f32 v212, v238, v239
	v_cvt_pk_bf16_f32 v213, v240, v241
	s_mov_b64 vcc, s[30:31]
	s_nop 0
	v_mov_b32_dpp v214, v212 quad_perm:[1,0,3,2] row_mask:0xf bank_mask:0xf
	v_mov_b32_dpp v215, v213 quad_perm:[1,0,3,2] row_mask:0xf bank_mask:0xf
	v_perm_b32 v216, v214, v212, v253
	v_perm_b32 v217, v215, v213, v253
	s_nop 1
	v_mov_b32_dpp v218, v216 quad_perm:[2,3,0,1] row_mask:0xf bank_mask:0xf
	v_mov_b32_dpp v219, v217 quad_perm:[2,3,0,1] row_mask:0xf bank_mask:0xf
	v_cndmask_b32_e32 v176, v216, v219, vcc
	v_cndmask_b32_e32 v177, v218, v217, vcc
	s_waitcnt lgkmcnt(0)
	s_mov_b64 vcc, s[28:29]
	v_cndmask_b32_e32 v208, v86, v94, vcc
	v_cndmask_b32_e32 v209, v87, v95, vcc
	v_cndmask_b32_e32 v210, v82, v90, vcc
	v_cndmask_b32_e32 v211, v83, v91, vcc
	ds_bpermute_b32 v200, v252, v208
	ds_bpermute_b32 v201, v252, v209
	ds_bpermute_b32 v202, v252, v210
	ds_bpermute_b32 v203, v252, v211
	v_pk_fma_f32 v[230:231], v[28:29], v[124:125], v[128:129] op_sel_hi:[1,0,0]
	v_pk_fma_f32 v[232:233], v[30:31], v[124:125], v[128:129] op_sel_hi:[1,0,0]
	v_fmac_f32_e32 v230, v205, v125
	v_fmac_f32_e32 v231, v28, v125
	v_fmac_f32_e32 v232, v29, v125
	v_fmac_f32_e32 v233, v30, v125
	v_pk_fma_f32 v[230:231], v[204:205], v[126:127], v[230:231] op_sel_hi:[1,0,1]
	v_pk_fma_f32 v[232:233], v[28:29], v[126:127], v[232:233] op_sel_hi:[1,0,1]
	v_pk_fma_f32 v[234:235], v[24:25], v[130:131], v[134:135] op_sel_hi:[1,0,0]
	v_pk_fma_f32 v[236:237], v[26:27], v[130:131], v[134:135] op_sel_hi:[1,0,0]
	v_fmac_f32_e32 v234, v207, v131
	v_fmac_f32_e32 v235, v24, v131
	v_fmac_f32_e32 v236, v25, v131
	v_fmac_f32_e32 v237, v26, v131
	v_pk_fma_f32 v[234:235], v[206:207], v[132:133], v[234:235] op_sel_hi:[1,0,1]
	v_pk_fma_f32 v[236:237], v[24:25], v[132:133], v[236:237] op_sel_hi:[1,0,1]
	v_pk_mul_f32 v[238:239], v[230:231], v[230:231]
	v_pk_mul_f32 v[240:241], v[232:233], v[232:233]
	v_pk_fma_f32 v[238:239], v[238:239], v[248:249], v[246:247]
	v_pk_fma_f32 v[240:241], v[240:241], v[248:249], v[246:247]
	v_pk_mul_f32 v[238:239], v[230:231], v[238:239]
	v_pk_mul_f32 v[240:241], v[232:233], v[240:241]
	v_exp_f32_e32 v238, v238
	v_exp_f32_e32 v239, v239
	v_exp_f32_e32 v240, v240
	v_exp_f32_e32 v241, v241
	v_pk_add_f32 v[238:239], v[238:239], 1.0 op_sel_hi:[1,0]
	v_pk_add_f32 v[240:241], v[240:241], 1.0 op_sel_hi:[1,0]
	v_rcp_f32_e32 v238, v238
	v_rcp_f32_e32 v239, v239
	v_rcp_f32_e32 v240, v240
	v_rcp_f32_e32 v241, v241
	v_pk_mul_f32 v[230:231], v[230:231], v[234:235]
	v_pk_mul_f32 v[232:233], v[232:233], v[236:237]
	v_pk_mul_f32 v[238:239], v[230:231], v[238:239]
	v_pk_mul_f32 v[240:241], v[232:233], v[240:241]
	v_cvt_pk_bf16_f32 v212, v238, v239
	v_cvt_pk_bf16_f32 v213, v240, v241
	s_mov_b64 vcc, s[30:31]
	s_nop 0
	v_mov_b32_dpp v214, v212 quad_perm:[1,0,3,2] row_mask:0xf bank_mask:0xf
	v_mov_b32_dpp v215, v213 quad_perm:[1,0,3,2] row_mask:0xf bank_mask:0xf
	v_perm_b32 v216, v214, v212, v253
	v_perm_b32 v217, v215, v213, v253
	s_nop 1
	v_mov_b32_dpp v218, v216 quad_perm:[2,3,0,1] row_mask:0xf bank_mask:0xf
	v_mov_b32_dpp v219, v217 quad_perm:[2,3,0,1] row_mask:0xf bank_mask:0xf
	v_cndmask_b32_e32 v178, v216, v219, vcc
	v_cndmask_b32_e32 v179, v218, v217, vcc
	s_movk_i32 s15, 0xf86
	v_cmp_gt_i32_e64 s[24:25], s15, v251
	s_add_u32 s84, s58, 0xa7c00
	s_addc_u32 s85, s59, 0
	s_and_b64 s[24:25], s[24:25], s[36:37]
	s_mov_b64 exec, s[24:25]
	global_store_dwordx4 v250, v[176:179], s[84:85] nt
	s_mov_b64 exec, -1
	s_nop 0
	s_waitcnt lgkmcnt(0)
	s_mov_b64 vcc, s[28:29]
	v_cndmask_b32_e32 v208, v22, v30, vcc
	v_cndmask_b32_e32 v209, v23, v31, vcc
	v_cndmask_b32_e32 v210, v18, v26, vcc
	v_cndmask_b32_e32 v211, v19, v27, vcc
	ds_bpermute_b32 v204, v252, v208
	ds_bpermute_b32 v205, v252, v209
	ds_bpermute_b32 v206, v252, v210
	ds_bpermute_b32 v207, v252, v211
	v_pk_fma_f32 v[230:231], v[84:85], v[112:113], v[116:117] op_sel_hi:[1,0,0]
	v_pk_fma_f32 v[232:233], v[86:87], v[112:113], v[116:117] op_sel_hi:[1,0,0]
	v_fmac_f32_e32 v230, v201, v113
	v_fmac_f32_e32 v231, v84, v113
	v_fmac_f32_e32 v232, v85, v113
	v_fmac_f32_e32 v233, v86, v113
	v_pk_fma_f32 v[230:231], v[200:201], v[114:115], v[230:231] op_sel_hi:[1,0,1]
	v_pk_fma_f32 v[232:233], v[84:85], v[114:115], v[232:233] op_sel_hi:[1,0,1]
	v_pk_fma_f32 v[234:235], v[80:81], v[118:119], v[122:123] op_sel_hi:[1,0,0]
	v_pk_fma_f32 v[236:237], v[82:83], v[118:119], v[122:123] op_sel_hi:[1,0,0]
	v_fmac_f32_e32 v234, v203, v119
	v_fmac_f32_e32 v235, v80, v119
	v_fmac_f32_e32 v236, v81, v119
	v_fmac_f32_e32 v237, v82, v119
	v_pk_fma_f32 v[234:235], v[202:203], v[120:121], v[234:235] op_sel_hi:[1,0,1]
	v_pk_fma_f32 v[236:237], v[80:81], v[120:121], v[236:237] op_sel_hi:[1,0,1]
	v_pk_mul_f32 v[238:239], v[230:231], v[230:231]
	v_pk_mul_f32 v[240:241], v[232:233], v[232:233]
	v_pk_fma_f32 v[238:239], v[238:239], v[248:249], v[246:247]
	v_pk_fma_f32 v[240:241], v[240:241], v[248:249], v[246:247]
	v_pk_mul_f32 v[238:239], v[230:231], v[238:239]
	v_pk_mul_f32 v[240:241], v[232:233], v[240:241]
	v_exp_f32_e32 v238, v238
	v_exp_f32_e32 v239, v239
	v_exp_f32_e32 v240, v240
	v_exp_f32_e32 v241, v241
	v_pk_add_f32 v[238:239], v[238:239], 1.0 op_sel_hi:[1,0]
	v_pk_add_f32 v[240:241], v[240:241], 1.0 op_sel_hi:[1,0]
	v_rcp_f32_e32 v238, v238
	v_rcp_f32_e32 v239, v239
	v_rcp_f32_e32 v240, v240
	v_rcp_f32_e32 v241, v241
	v_pk_mul_f32 v[230:231], v[230:231], v[234:235]
	v_pk_mul_f32 v[232:233], v[232:233], v[236:237]
	v_pk_mul_f32 v[238:239], v[230:231], v[238:239]
	v_pk_mul_f32 v[240:241], v[232:233], v[240:241]
	v_cvt_pk_bf16_f32 v212, v238, v239
	v_cvt_pk_bf16_f32 v213, v240, v241
	s_mov_b64 vcc, s[30:31]
	s_nop 0
	v_mov_b32_dpp v214, v212 quad_perm:[1,0,3,2] row_mask:0xf bank_mask:0xf
	v_mov_b32_dpp v215, v213 quad_perm:[1,0,3,2] row_mask:0xf bank_mask:0xf
	v_perm_b32 v216, v214, v212, v253
	v_perm_b32 v217, v215, v213, v253
	s_nop 1
	v_mov_b32_dpp v218, v216 quad_perm:[2,3,0,1] row_mask:0xf bank_mask:0xf
	v_mov_b32_dpp v219, v217 quad_perm:[2,3,0,1] row_mask:0xf bank_mask:0xf
	v_cndmask_b32_e32 v180, v216, v219, vcc
	v_cndmask_b32_e32 v181, v218, v217, vcc
	s_waitcnt lgkmcnt(0)
	s_mov_b64 vcc, s[28:29]
	v_cndmask_b32_e32 v208, v78, v86, vcc
	v_cndmask_b32_e32 v209, v79, v87, vcc
	v_cndmask_b32_e32 v210, v74, v82, vcc
	v_cndmask_b32_e32 v211, v75, v83, vcc
	ds_bpermute_b32 v200, v252, v208
	ds_bpermute_b32 v201, v252, v209
	ds_bpermute_b32 v202, v252, v210
	ds_bpermute_b32 v203, v252, v211
	v_pk_fma_f32 v[230:231], v[20:21], v[124:125], v[128:129] op_sel_hi:[1,0,0]
	v_pk_fma_f32 v[232:233], v[22:23], v[124:125], v[128:129] op_sel_hi:[1,0,0]
	v_fmac_f32_e32 v230, v205, v125
	v_fmac_f32_e32 v231, v20, v125
	v_fmac_f32_e32 v232, v21, v125
	v_fmac_f32_e32 v233, v22, v125
	v_pk_fma_f32 v[230:231], v[204:205], v[126:127], v[230:231] op_sel_hi:[1,0,1]
	v_pk_fma_f32 v[232:233], v[20:21], v[126:127], v[232:233] op_sel_hi:[1,0,1]
	v_pk_fma_f32 v[234:235], v[16:17], v[130:131], v[134:135] op_sel_hi:[1,0,0]
	v_pk_fma_f32 v[236:237], v[18:19], v[130:131], v[134:135] op_sel_hi:[1,0,0]
	v_fmac_f32_e32 v234, v207, v131
	v_fmac_f32_e32 v235, v16, v131
	v_fmac_f32_e32 v236, v17, v131
	v_fmac_f32_e32 v237, v18, v131
	v_pk_fma_f32 v[234:235], v[206:207], v[132:133], v[234:235] op_sel_hi:[1,0,1]
	v_pk_fma_f32 v[236:237], v[16:17], v[132:133], v[236:237] op_sel_hi:[1,0,1]
	v_pk_mul_f32 v[238:239], v[230:231], v[230:231]
	v_pk_mul_f32 v[240:241], v[232:233], v[232:233]
	v_pk_fma_f32 v[238:239], v[238:239], v[248:249], v[246:247]
	v_pk_fma_f32 v[240:241], v[240:241], v[248:249], v[246:247]
	v_pk_mul_f32 v[238:239], v[230:231], v[238:239]
	v_pk_mul_f32 v[240:241], v[232:233], v[240:241]
	v_exp_f32_e32 v238, v238
	v_exp_f32_e32 v239, v239
	v_exp_f32_e32 v240, v240
	v_exp_f32_e32 v241, v241
	v_pk_add_f32 v[238:239], v[238:239], 1.0 op_sel_hi:[1,0]
	v_pk_add_f32 v[240:241], v[240:241], 1.0 op_sel_hi:[1,0]
	v_rcp_f32_e32 v238, v238
	v_rcp_f32_e32 v239, v239
	v_rcp_f32_e32 v240, v240
	v_rcp_f32_e32 v241, v241
	v_pk_mul_f32 v[230:231], v[230:231], v[234:235]
	v_pk_mul_f32 v[232:233], v[232:233], v[236:237]
	v_pk_mul_f32 v[238:239], v[230:231], v[238:239]
	v_pk_mul_f32 v[240:241], v[232:233], v[240:241]
	v_cvt_pk_bf16_f32 v212, v238, v239
	v_cvt_pk_bf16_f32 v213, v240, v241
	s_mov_b64 vcc, s[30:31]
	s_nop 0
	v_mov_b32_dpp v214, v212 quad_perm:[1,0,3,2] row_mask:0xf bank_mask:0xf
	v_mov_b32_dpp v215, v213 quad_perm:[1,0,3,2] row_mask:0xf bank_mask:0xf
	v_perm_b32 v216, v214, v212, v253
	v_perm_b32 v217, v215, v213, v253
	s_nop 1
	v_mov_b32_dpp v218, v216 quad_perm:[2,3,0,1] row_mask:0xf bank_mask:0xf
	v_mov_b32_dpp v219, v217 quad_perm:[2,3,0,1] row_mask:0xf bank_mask:0xf
	v_cndmask_b32_e32 v182, v216, v219, vcc
	v_cndmask_b32_e32 v183, v218, v217, vcc
	s_movk_i32 s15, 0xf76
	v_cmp_gt_i32_e64 s[24:25], s15, v251
	s_add_u32 s84, s58, 0xbdc00
	s_addc_u32 s85, s59, 0
	s_mov_b64 exec, s[24:25]
	global_store_dwordx4 v250, v[180:183], s[84:85] nt
	s_mov_b64 exec, -1
	s_nop 0
	s_waitcnt lgkmcnt(0)
	s_mov_b64 vcc, s[28:29]
	v_cndmask_b32_e32 v208, v14, v22, vcc
	v_cndmask_b32_e32 v209, v15, v23, vcc
	v_cndmask_b32_e32 v210, v10, v18, vcc
	v_cndmask_b32_e32 v211, v11, v19, vcc
	ds_bpermute_b32 v204, v252, v208
	ds_bpermute_b32 v205, v252, v209
	ds_bpermute_b32 v206, v252, v210
	ds_bpermute_b32 v207, v252, v211
	v_pk_fma_f32 v[230:231], v[76:77], v[112:113], v[116:117] op_sel_hi:[1,0,0]
	v_pk_fma_f32 v[232:233], v[78:79], v[112:113], v[116:117] op_sel_hi:[1,0,0]
	v_fmac_f32_e32 v230, v201, v113
	v_fmac_f32_e32 v231, v76, v113
	v_fmac_f32_e32 v232, v77, v113
	v_fmac_f32_e32 v233, v78, v113
	v_pk_fma_f32 v[230:231], v[200:201], v[114:115], v[230:231] op_sel_hi:[1,0,1]
	v_pk_fma_f32 v[232:233], v[76:77], v[114:115], v[232:233] op_sel_hi:[1,0,1]
	v_pk_fma_f32 v[234:235], v[72:73], v[118:119], v[122:123] op_sel_hi:[1,0,0]
	v_pk_fma_f32 v[236:237], v[74:75], v[118:119], v[122:123] op_sel_hi:[1,0,0]
	v_fmac_f32_e32 v234, v203, v119
	v_fmac_f32_e32 v235, v72, v119
	v_fmac_f32_e32 v236, v73, v119
	v_fmac_f32_e32 v237, v74, v119
	v_pk_fma_f32 v[234:235], v[202:203], v[120:121], v[234:235] op_sel_hi:[1,0,1]
	v_pk_fma_f32 v[236:237], v[72:73], v[120:121], v[236:237] op_sel_hi:[1,0,1]
	v_pk_mul_f32 v[238:239], v[230:231], v[230:231]
	v_pk_mul_f32 v[240:241], v[232:233], v[232:233]
	v_pk_fma_f32 v[238:239], v[238:239], v[248:249], v[246:247]
	v_pk_fma_f32 v[240:241], v[240:241], v[248:249], v[246:247]
	v_pk_mul_f32 v[238:239], v[230:231], v[238:239]
	v_pk_mul_f32 v[240:241], v[232:233], v[240:241]
	v_exp_f32_e32 v238, v238
	v_exp_f32_e32 v239, v239
	v_exp_f32_e32 v240, v240
	v_exp_f32_e32 v241, v241
	v_pk_add_f32 v[238:239], v[238:239], 1.0 op_sel_hi:[1,0]
	v_pk_add_f32 v[240:241], v[240:241], 1.0 op_sel_hi:[1,0]
	v_rcp_f32_e32 v238, v238
	v_rcp_f32_e32 v239, v239
	v_rcp_f32_e32 v240, v240
	v_rcp_f32_e32 v241, v241
	v_pk_mul_f32 v[230:231], v[230:231], v[234:235]
	v_pk_mul_f32 v[232:233], v[232:233], v[236:237]
	v_pk_mul_f32 v[238:239], v[230:231], v[238:239]
	v_pk_mul_f32 v[240:241], v[232:233], v[240:241]
	v_cvt_pk_bf16_f32 v212, v238, v239
	v_cvt_pk_bf16_f32 v213, v240, v241
	s_mov_b64 vcc, s[30:31]
	s_nop 0
	v_mov_b32_dpp v214, v212 quad_perm:[1,0,3,2] row_mask:0xf bank_mask:0xf
	v_mov_b32_dpp v215, v213 quad_perm:[1,0,3,2] row_mask:0xf bank_mask:0xf
	v_perm_b32 v216, v214, v212, v253
	v_perm_b32 v217, v215, v213, v253
	s_nop 1
	v_mov_b32_dpp v218, v216 quad_perm:[2,3,0,1] row_mask:0xf bank_mask:0xf
	v_mov_b32_dpp v219, v217 quad_perm:[2,3,0,1] row_mask:0xf bank_mask:0xf
	v_cndmask_b32_e32 v176, v216, v219, vcc
	v_cndmask_b32_e32 v177, v218, v217, vcc
	s_waitcnt lgkmcnt(0)
	s_mov_b64 vcc, s[28:29]
	v_cndmask_b32_e32 v208, v70, v78, vcc
	v_cndmask_b32_e32 v209, v71, v79, vcc
	v_cndmask_b32_e32 v210, v66, v74, vcc
	v_cndmask_b32_e32 v211, v67, v75, vcc
	ds_bpermute_b32 v200, v252, v208
	ds_bpermute_b32 v201, v252, v209
	ds_bpermute_b32 v202, v252, v210
	ds_bpermute_b32 v203, v252, v211
	v_pk_fma_f32 v[230:231], v[12:13], v[124:125], v[128:129] op_sel_hi:[1,0,0]
	v_pk_fma_f32 v[232:233], v[14:15], v[124:125], v[128:129] op_sel_hi:[1,0,0]
	v_fmac_f32_e32 v230, v205, v125
	v_fmac_f32_e32 v231, v12, v125
	v_fmac_f32_e32 v232, v13, v125
	v_fmac_f32_e32 v233, v14, v125
	v_pk_fma_f32 v[230:231], v[204:205], v[126:127], v[230:231] op_sel_hi:[1,0,1]
	v_pk_fma_f32 v[232:233], v[12:13], v[126:127], v[232:233] op_sel_hi:[1,0,1]
	v_pk_fma_f32 v[234:235], v[8:9], v[130:131], v[134:135] op_sel_hi:[1,0,0]
	v_pk_fma_f32 v[236:237], v[10:11], v[130:131], v[134:135] op_sel_hi:[1,0,0]
	v_fmac_f32_e32 v234, v207, v131
	v_fmac_f32_e32 v235, v8, v131
	v_fmac_f32_e32 v236, v9, v131
	v_fmac_f32_e32 v237, v10, v131
	v_pk_fma_f32 v[234:235], v[206:207], v[132:133], v[234:235] op_sel_hi:[1,0,1]
	v_pk_fma_f32 v[236:237], v[8:9], v[132:133], v[236:237] op_sel_hi:[1,0,1]
	v_pk_mul_f32 v[238:239], v[230:231], v[230:231]
	v_pk_mul_f32 v[240:241], v[232:233], v[232:233]
	v_pk_fma_f32 v[238:239], v[238:239], v[248:249], v[246:247]
	v_pk_fma_f32 v[240:241], v[240:241], v[248:249], v[246:247]
	v_pk_mul_f32 v[238:239], v[230:231], v[238:239]
	v_pk_mul_f32 v[240:241], v[232:233], v[240:241]
	v_exp_f32_e32 v238, v238
	v_exp_f32_e32 v239, v239
	v_exp_f32_e32 v240, v240
	v_exp_f32_e32 v241, v241
	v_pk_add_f32 v[238:239], v[238:239], 1.0 op_sel_hi:[1,0]
	v_pk_add_f32 v[240:241], v[240:241], 1.0 op_sel_hi:[1,0]
	v_rcp_f32_e32 v238, v238
	v_rcp_f32_e32 v239, v239
	v_rcp_f32_e32 v240, v240
	v_rcp_f32_e32 v241, v241
	v_pk_mul_f32 v[230:231], v[230:231], v[234:235]
	v_pk_mul_f32 v[232:233], v[232:233], v[236:237]
	v_pk_mul_f32 v[238:239], v[230:231], v[238:239]
	v_pk_mul_f32 v[240:241], v[232:233], v[240:241]
	v_cvt_pk_bf16_f32 v212, v238, v239
	v_cvt_pk_bf16_f32 v213, v240, v241
	s_mov_b64 vcc, s[30:31]
	s_nop 0
	v_mov_b32_dpp v214, v212 quad_perm:[1,0,3,2] row_mask:0xf bank_mask:0xf
	v_mov_b32_dpp v215, v213 quad_perm:[1,0,3,2] row_mask:0xf bank_mask:0xf
	v_perm_b32 v216, v214, v212, v253
	v_perm_b32 v217, v215, v213, v253
	s_nop 1
	v_mov_b32_dpp v218, v216 quad_perm:[2,3,0,1] row_mask:0xf bank_mask:0xf
	v_mov_b32_dpp v219, v217 quad_perm:[2,3,0,1] row_mask:0xf bank_mask:0xf
	v_cndmask_b32_e32 v178, v216, v219, vcc
	v_cndmask_b32_e32 v179, v218, v217, vcc
	s_movk_i32 s15, 0xf66
	v_cmp_gt_i32_e64 s[24:25], s15, v251
	s_add_u32 s84, s58, 0xd3c00
	s_addc_u32 s85, s59, 0
	s_mov_b64 exec, s[24:25]
	global_store_dwordx4 v250, v[176:179], s[84:85] nt
	s_mov_b64 exec, -1
	s_nop 0
	s_waitcnt lgkmcnt(0)
	s_mov_b64 vcc, s[28:29]
	v_cndmask_b32_e32 v208, v6, v14, vcc
	v_cndmask_b32_e32 v209, v7, v15, vcc
	v_cndmask_b32_e32 v210, v2, v10, vcc
	v_cndmask_b32_e32 v211, v3, v11, vcc
	ds_bpermute_b32 v204, v252, v208
	ds_bpermute_b32 v205, v252, v209
	ds_bpermute_b32 v206, v252, v210
	ds_bpermute_b32 v207, v252, v211
	v_pk_fma_f32 v[230:231], v[68:69], v[112:113], v[116:117] op_sel_hi:[1,0,0]
	v_pk_fma_f32 v[232:233], v[70:71], v[112:113], v[116:117] op_sel_hi:[1,0,0]
	v_fmac_f32_e32 v230, v201, v113
	v_fmac_f32_e32 v231, v68, v113
	v_fmac_f32_e32 v232, v69, v113
	v_fmac_f32_e32 v233, v70, v113
	v_pk_fma_f32 v[230:231], v[200:201], v[114:115], v[230:231] op_sel_hi:[1,0,1]
	v_pk_fma_f32 v[232:233], v[68:69], v[114:115], v[232:233] op_sel_hi:[1,0,1]
	v_pk_fma_f32 v[234:235], v[64:65], v[118:119], v[122:123] op_sel_hi:[1,0,0]
	v_pk_fma_f32 v[236:237], v[66:67], v[118:119], v[122:123] op_sel_hi:[1,0,0]
	v_fmac_f32_e32 v234, v203, v119
	v_fmac_f32_e32 v235, v64, v119
	v_fmac_f32_e32 v236, v65, v119
	v_fmac_f32_e32 v237, v66, v119
	v_pk_fma_f32 v[234:235], v[202:203], v[120:121], v[234:235] op_sel_hi:[1,0,1]
	v_pk_fma_f32 v[236:237], v[64:65], v[120:121], v[236:237] op_sel_hi:[1,0,1]
	v_pk_mul_f32 v[238:239], v[230:231], v[230:231]
	v_pk_mul_f32 v[240:241], v[232:233], v[232:233]
	v_pk_fma_f32 v[238:239], v[238:239], v[248:249], v[246:247]
	v_pk_fma_f32 v[240:241], v[240:241], v[248:249], v[246:247]
	v_pk_mul_f32 v[238:239], v[230:231], v[238:239]
	v_pk_mul_f32 v[240:241], v[232:233], v[240:241]
	v_exp_f32_e32 v238, v238
	v_exp_f32_e32 v239, v239
	v_exp_f32_e32 v240, v240
	v_exp_f32_e32 v241, v241
	v_pk_add_f32 v[238:239], v[238:239], 1.0 op_sel_hi:[1,0]
	v_pk_add_f32 v[240:241], v[240:241], 1.0 op_sel_hi:[1,0]
	v_rcp_f32_e32 v238, v238
	v_rcp_f32_e32 v239, v239
	v_rcp_f32_e32 v240, v240
	v_rcp_f32_e32 v241, v241
	v_pk_mul_f32 v[230:231], v[230:231], v[234:235]
	v_pk_mul_f32 v[232:233], v[232:233], v[236:237]
	v_pk_mul_f32 v[238:239], v[230:231], v[238:239]
	v_pk_mul_f32 v[240:241], v[232:233], v[240:241]
	v_cvt_pk_bf16_f32 v212, v238, v239
	v_cvt_pk_bf16_f32 v213, v240, v241
	s_mov_b64 vcc, s[30:31]
	s_nop 0
	v_mov_b32_dpp v214, v212 quad_perm:[1,0,3,2] row_mask:0xf bank_mask:0xf
	v_mov_b32_dpp v215, v213 quad_perm:[1,0,3,2] row_mask:0xf bank_mask:0xf
	v_perm_b32 v216, v214, v212, v253
	v_perm_b32 v217, v215, v213, v253
	s_nop 1
	v_mov_b32_dpp v218, v216 quad_perm:[2,3,0,1] row_mask:0xf bank_mask:0xf
	v_mov_b32_dpp v219, v217 quad_perm:[2,3,0,1] row_mask:0xf bank_mask:0xf
	v_cndmask_b32_e32 v180, v216, v219, vcc
	v_cndmask_b32_e32 v181, v218, v217, vcc
	s_waitcnt lgkmcnt(0)
	v_pk_fma_f32 v[230:231], v[4:5], v[124:125], v[128:129] op_sel_hi:[1,0,0]
	v_pk_fma_f32 v[232:233], v[6:7], v[124:125], v[128:129] op_sel_hi:[1,0,0]
	v_fmac_f32_e32 v230, v205, v125
	v_fmac_f32_e32 v231, v4, v125
	v_fmac_f32_e32 v232, v5, v125
	v_fmac_f32_e32 v233, v6, v125
	v_pk_fma_f32 v[230:231], v[204:205], v[126:127], v[230:231] op_sel_hi:[1,0,1]
	v_pk_fma_f32 v[232:233], v[4:5], v[126:127], v[232:233] op_sel_hi:[1,0,1]
	v_pk_fma_f32 v[234:235], v[0:1], v[130:131], v[134:135] op_sel_hi:[1,0,0]
	v_pk_fma_f32 v[236:237], v[2:3], v[130:131], v[134:135] op_sel_hi:[1,0,0]
	v_fmac_f32_e32 v234, v207, v131
	v_fmac_f32_e32 v235, v0, v131
	v_fmac_f32_e32 v236, v1, v131
	v_fmac_f32_e32 v237, v2, v131
	v_pk_fma_f32 v[234:235], v[206:207], v[132:133], v[234:235] op_sel_hi:[1,0,1]
	v_pk_fma_f32 v[236:237], v[0:1], v[132:133], v[236:237] op_sel_hi:[1,0,1]
	v_pk_mul_f32 v[238:239], v[230:231], v[230:231]
	v_pk_mul_f32 v[240:241], v[232:233], v[232:233]
	v_pk_fma_f32 v[238:239], v[238:239], v[248:249], v[246:247]
	v_pk_fma_f32 v[240:241], v[240:241], v[248:249], v[246:247]
	v_pk_mul_f32 v[238:239], v[230:231], v[238:239]
	v_pk_mul_f32 v[240:241], v[232:233], v[240:241]
	v_exp_f32_e32 v238, v238
	v_exp_f32_e32 v239, v239
	v_exp_f32_e32 v240, v240
	v_exp_f32_e32 v241, v241
	v_pk_add_f32 v[238:239], v[238:239], 1.0 op_sel_hi:[1,0]
	v_pk_add_f32 v[240:241], v[240:241], 1.0 op_sel_hi:[1,0]
	v_rcp_f32_e32 v238, v238
	v_rcp_f32_e32 v239, v239
	v_rcp_f32_e32 v240, v240
	v_rcp_f32_e32 v241, v241
	v_pk_mul_f32 v[230:231], v[230:231], v[234:235]
	v_pk_mul_f32 v[232:233], v[232:233], v[236:237]
	v_pk_mul_f32 v[238:239], v[230:231], v[238:239]
	v_pk_mul_f32 v[240:241], v[232:233], v[240:241]
	v_cvt_pk_bf16_f32 v212, v238, v239
	v_cvt_pk_bf16_f32 v213, v240, v241
	s_mov_b64 vcc, s[30:31]
	s_nop 0
	v_mov_b32_dpp v214, v212 quad_perm:[1,0,3,2] row_mask:0xf bank_mask:0xf
	v_mov_b32_dpp v215, v213 quad_perm:[1,0,3,2] row_mask:0xf bank_mask:0xf
	v_perm_b32 v216, v214, v212, v253
	v_perm_b32 v217, v215, v213, v253
	s_nop 1
	v_mov_b32_dpp v218, v216 quad_perm:[2,3,0,1] row_mask:0xf bank_mask:0xf
	v_mov_b32_dpp v219, v217 quad_perm:[2,3,0,1] row_mask:0xf bank_mask:0xf
	v_cndmask_b32_e32 v182, v216, v219, vcc
	v_cndmask_b32_e32 v183, v218, v217, vcc
	s_movk_i32 s15, 0xf56
	v_cmp_gt_i32_e64 s[24:25], s15, v251
	s_add_u32 s84, s58, 0xe9c00
	s_addc_u32 s85, s59, 0
	s_mov_b64 exec, s[24:25]
	global_store_dwordx4 v250, v[180:183], s[84:85] nt
	s_mov_b64 exec, -1
	s_nop 0
	s_mov_b64 s[0:1], -1
	s_branch .LBB0_619
	s_nop 0
	s_nop 0
	s_nop 0
	s_nop 0
	s_nop 0
	s_nop 0
	s_nop 0
	s_nop 0
	s_nop 0
	s_nop 0
	s_nop 0
	s_nop 0
	s_nop 0
	s_nop 0
	s_nop 0
	s_nop 0
	s_nop 0
	s_nop 0
	s_nop 0
	s_nop 0
	s_nop 0
	s_nop 0
	s_nop 0
	s_nop 0
	s_nop 0
	s_nop 0
	s_nop 0
	s_nop 0
	s_nop 0
	s_nop 0
	s_nop 0
	s_nop 0
	s_nop 0
	s_nop 0
	s_nop 0
	s_nop 0
	s_nop 0
	s_nop 0
	s_nop 0
	s_nop 0
	s_nop 0
	s_nop 0
	s_nop 0
	s_nop 0
	s_nop 0
	s_nop 0
	s_nop 0
	s_nop 0
	s_nop 0
	s_nop 0
	s_nop 0
	s_nop 0
	s_nop 0
	s_nop 0
	s_nop 0
	s_nop 0
	s_nop 0
	s_nop 0
	s_nop 0
	s_nop 0
	s_nop 0
	s_nop 0
	s_nop 0
	s_nop 0
	s_nop 0
	s_nop 0
	s_nop 0
	s_nop 0
	s_nop 0
	s_nop 0
	s_nop 0
	s_nop 0
	s_nop 0
	s_nop 0
	s_nop 0
	s_nop 0
	s_nop 0
	s_nop 0
	s_nop 0
	s_nop 0
	s_nop 0
	s_nop 0
	s_nop 0
	s_nop 0
	s_nop 0
	s_nop 0
	s_nop 0
	s_nop 0
	s_nop 0
	s_nop 0
	s_nop 0
	s_nop 0
	s_nop 0
	s_nop 0
	s_nop 0
	s_nop 0
	s_nop 0
	s_nop 0
	s_nop 0
	s_nop 0
	s_nop 0
	s_nop 0
	s_nop 0
	s_nop 0
	s_nop 0
	s_nop 0
	s_nop 0
	s_nop 0
	s_nop 0
	s_nop 0
	s_nop 0
	s_nop 0
	s_nop 0
	s_nop 0
	s_nop 0
	s_nop 0
	s_nop 0
	s_nop 0
	s_nop 0
	s_nop 0
	s_nop 0
	s_nop 0
	s_nop 0
	s_nop 0
	s_nop 0
	s_nop 0
	s_nop 0
	s_nop 0
	s_nop 0
	s_nop 0
	s_nop 0
	s_nop 0
	s_nop 0
	s_nop 0
	s_nop 0
	s_nop 0
	s_nop 0
	s_nop 0
	s_nop 0
	s_nop 0
	s_nop 0
	s_nop 0
	s_nop 0
	s_nop 0
	s_nop 0
	s_nop 0
	s_nop 0
	s_nop 0
	s_nop 0
	s_nop 0
	s_nop 0
	s_nop 0
	s_nop 0
	s_nop 0
	s_nop 0
	s_nop 0
	s_nop 0
	s_nop 0
	s_nop 0
	s_nop 0
	s_nop 0
	s_nop 0
	s_nop 0
	s_nop 0
	s_nop 0
	s_nop 0
	s_nop 0
	s_nop 0
	s_nop 0
	s_nop 0
	s_nop 0
	s_nop 0
	s_nop 0
